# MLA loop: row-sum additions of the exponentials issued between the last four PV MFMAs instead of after them (same operations and order)
# speedup vs baseline: 1.0009x; 1.0009x over previous
.LBB0_349:
	v_pk_add_f32 v[66:67], v[66:67], v[70:71]
	v_pk_add_f32 v[74:75], v[74:75], v[78:79]
	v_pk_add_f32 v[66:67], v[66:67], v[74:75]
	v_add_f32_e32 v202, v202, v66
	v_add_f32_e32 v202, v202, v67
	s_add_i32 s2, s2, 1
	v_add_f32_e32 v163, v163, v202
	v_add_u32_e32 v114, 64, v114
	v_add_u32_e32 v170, 64, v170
	s_add_i32 s0, s2, -1
	s_and_b32 s0, s0, 1
	s_mulk_i32 s0, 0x5100
	s_add_i32 s101, s100, s0
	v_mov_b32_e32 v218, v170
	v_ashrrev_i32_e32 v219, 31, v170
	v_lshlrev_b64 v[216:217], 11, v[218:219]
	v_lshlrev_b64 v[218:219], 9, v[218:219]
	v_lshl_add_u64 v[216:217], s[10:11], 0, v[216:217]
	v_lshl_add_u64 v[218:219], s[12:13], 0, v[218:219]
	s_cmp_eq_u32 s22, s2
	s_waitcnt vmcnt(0)
	s_waitcnt lgkmcnt(0)
	s_barrier
	s_cbranch_scc1 .LBB0_358

.LBB0_356:
	v_exp_f32_e32 v115, v2
	v_exp_f32_e32 v171, v3
	v_exp_f32_e32 v200, v4
	v_exp_f32_e32 v201, v5
	v_exp_f32_e32 v6, v6
	v_exp_f32_e32 v7, v7
	v_exp_f32_e32 v8, v8
	v_exp_f32_e32 v9, v9
	v_cvt_pk_bf16_f32 v202, v115, v171
	v_cvt_pk_bf16_f32 v203, v200, v201
	v_cvt_pk_bf16_f32 v204, v6, v7
	v_cvt_pk_bf16_f32 v205, v8, v9
	v_exp_f32_e32 v10, v10
	v_exp_f32_e32 v11, v11
	v_exp_f32_e32 v12, v12
	v_exp_f32_e32 v13, v13
	v_exp_f32_e32 v14, v14
	v_exp_f32_e32 v15, v15
	v_exp_f32_e32 v16, v16
	v_exp_f32_e32 v17, v17
	v_mfma_f32_32x32x16_bf16 v[32:47], v[202:205], v[152:155], v[32:47]
	v_cvt_pk_bf16_f32 v206, v10, v11
	v_cvt_pk_bf16_f32 v207, v12, v13
	v_cvt_pk_bf16_f32 v208, v14, v15
	v_cvt_pk_bf16_f32 v209, v16, v17
	v_exp_f32_e32 v64, v64
	v_exp_f32_e32 v65, v65
	v_exp_f32_e32 v66, v66
	s_waitcnt lgkmcnt(6)
	v_mfma_f32_32x32x16_bf16 v[48:63], v[202:205], v[92:95], v[48:63]
	v_exp_f32_e32 v67, v67
	v_exp_f32_e32 v68, v68
	v_exp_f32_e32 v69, v69
	v_exp_f32_e32 v70, v70
	v_exp_f32_e32 v71, v71
	v_cvt_pk_bf16_f32 v210, v64, v65
	v_cvt_pk_bf16_f32 v211, v66, v67
	v_mfma_f32_32x32x16_bf16 v[32:47], v[206:209], v[88:91], v[32:47]
	v_cvt_pk_bf16_f32 v212, v68, v69
	v_cvt_pk_bf16_f32 v213, v70, v71
	v_exp_f32_e32 v72, v72
	v_exp_f32_e32 v73, v73
	v_exp_f32_e32 v74, v74
	v_exp_f32_e32 v75, v75
	v_exp_f32_e32 v76, v76
	s_waitcnt lgkmcnt(4)
	v_mfma_f32_32x32x16_bf16 v[48:63], v[206:209], v[84:87], v[48:63]
	v_exp_f32_e32 v77, v77
	v_exp_f32_e32 v78, v78
	v_exp_f32_e32 v79, v79
	v_cvt_pk_bf16_f32 v2, v72, v73
	v_cvt_pk_bf16_f32 v3, v74, v75
	v_cvt_pk_bf16_f32 v4, v76, v77
	v_cvt_pk_bf16_f32 v5, v78, v79
	v_mfma_f32_32x32x16_bf16 v[32:47], v[210:213], v[80:83], v[32:47]
	s_mulk_i32 s3, 0x5100
	s_and_b64 vcc, exec, s[38:39]
	v_pk_add_f32 v[66:67], v[66:67], v[200:201]
	v_pk_add_f32 v[68:69], v[68:69], v[6:7]
	v_pk_add_f32 v[70:71], v[70:71], v[8:9]
	v_pk_add_f32 v[72:73], v[72:73], v[10:11]
	s_waitcnt lgkmcnt(2)
	v_mfma_f32_32x32x16_bf16 v[48:63], v[210:213], v[26:29], v[48:63]
	v_pk_add_f32 v[74:75], v[74:75], v[12:13]
	v_pk_add_f32 v[76:77], v[76:77], v[14:15]
	v_pk_add_f32 v[78:79], v[78:79], v[16:17]
	v_add_f32_e32 v202, v64, v115
	v_add_f32_e32 v203, v65, v171
	v_mfma_f32_32x32x16_bf16 v[32:47], v[2:5], v[18:21], v[32:47]
	v_pk_add_f32 v[66:67], v[66:67], v[68:69]
	v_pk_add_f32 v[70:71], v[70:71], v[72:73]
	v_pk_add_f32 v[74:75], v[74:75], v[76:77]
	v_add_f32_e32 v202, v202, v203
	s_waitcnt lgkmcnt(0)
	v_mfma_f32_32x32x16_bf16 v[48:63], v[2:5], v[22:25], v[48:63]
	s_branch .LBB0_349
